# branch B unit body rewritten by hand: batched QK / softmax / PV phases, non-online softmax over the 32 valid scores per lane, bias folded into MFMA accumulator init
# speedup vs baseline: 1.0273x; 1.0121x over previous
; __device__ __forceinline__ void attn_b_unit(LAS unsigned char* lds, const bf16* Z, bf16* Y, int unit) {
;     const int tid = threadIdx.x, lane = tid & 63, wid = tid >> 6, lq = lane & 15, g = lane >> 4;
;     const int rp = unit & 63, h = (unit >> 6) & 7, b = unit >> 9;
;     const size_t tok0 = (size_t)b * SEQ;
;     const int R0 = clampi(2 * rp - 4, 0, 120);
;     LAS unsigned char* Kl = lds + B_KOFF; LAS unsigned char* Vl = lds + B_VOFF; LAS float* T = (LAS float*)(lds + B_TOFF);
;     const int rq = 2 * rp + (wid >> 2), cb = wid & 3, c = 16 * cb + lq;
;     const int r0q = clampi(rq - 4, 0, 120), kc0 = clampi(16 * cb - 8, 0, 32), cs = clampi(c - 8, 0, 48);
;     const size_t qtok = tok0 + (size_t)rq * 64 + c;
;     const unsigned char* qp = (const unsigned char*)Z + tmo((int)qtok, Z_QB / 64 + h, ZLD / 64) + 16 * g;
;     const bf16x8 qf0 = *(const bf16x8*)qp, qf1 = *(const bf16x8*)(qp + 64);
;     float m0 = -1e30f, l0 = 0.f, m1 = -1e30f, l1 = 0.f;
;     f32x4 O0[4], O1[4];
; #pragma unroll
;     for (int d = 0; d < 4; ++d) { O0[d] = (f32x4){0.f, 0.f, 0.f, 0.f}; O1[d] = (f32x4){0.f, 0.f, 0.f, 0.f}; }
;     const int kcl = kc0 + 4 * g;
;     const int tb = 16 + (kcl - c + 15);
;     const int Rb = (r0q - R0) * 64 + kc0;
;     const LAS unsigned char* kp0 = Kl + swz(Rb + lq, g); const LAS unsigned char* kp1 = Kl + swz(Rb + lq, 4 + g);
;     const LAS unsigned char* vp[4];
;     { const int i = lane & 15, rq4 = i >> 2, p = i & 3;
; #pragma unroll
;       for (int db = 0; db < 4; ++db) vp[db] = Vl + swz(Rb + 4 * g + rq4, 2 * db + (p >> 1)) + 8 * (p & 1); }
;     const LAS float* T0 = T + tb + (r0q - rq + 7) * 32;
;     const LAS float* tpa[4]; const LAS float* tpb[4];
; #pragma unroll
;     for (int r = 0; r < 4; ++r) { const int kca = kcl + r, kcb = kca + 16;
;         tpa[r] = (kca >= cs && kca <= cs + 15) ? T0 + r : T + B_TREAL; tpb[r] = (kcb >= cs && kcb <= cs + 15) ? T0 + 16 + r : T + B_TREAL; }
; #pragma unroll
;     for (int st = 0; st < 4; ++st) {
;         const int offA = st * 8192, offB = offA + 4 * 8192;
;         f32x4 SA0, SA1, SB0, SB1;
;         qk_at(kp0, kp1, offA, qf0, qf1, SA0, SA1);
;         qk_at(kp0, kp1, offB, qf0, qf1, SB0, SB1);
; #pragma unroll
;         for (int r = 0; r < 4; ++r) {
;             SA0[r] += tpa[r][st * 32]; SA1[r] += tpb[r][st * 32]; SB0[r] += tpa[r][st * 32 + 128]; SB1[r] += tpb[r][st * 32 + 128];
;         }
.LBB0_280:
	s_and_b32 s51, s58, 0x7e
	v_add_u32_e32 v61, s51, v115
	s_and_b32 s26, s59, 0xffffe000
	v_lshlrev_b32_e32 v58, 6, v61
	v_add_u32_e32 v60, s26, v58
	s_bfe_u32 s50, s72, 0x30006
	v_ashrrev_i32_e32 v60, 8, v60
	v_or_b32_e32 v58, v58, v116
	v_lshlrev_b32_e32 v58, 7, v58
	v_and_b32_e32 v58, 0x7f80, v58
	v_sub_co_u32_e64 v100, s[58:59], s51, 4
	v_subrev_co_u32_e32 v101, vcc, 4, v61
	v_min_u32_e32 v100, 0x78, v100
	v_min_u32_e32 v101, 0x78, v101
	v_cndmask_b32_e64 v100, v100, 0, s[58:59]
	v_cndmask_b32_e64 v101, v101, 0, vcc
	v_sub_u32_e32 v100, v101, v100
	v_lshl_or_b32 v100, v100, 6, v117
	v_sub_u32_e32 v61, v101, v61
	v_add_u32_e32 v101, v100, v113
	v_add_u32_e32 v216, v100, v119
	v_bitop3_b32 v100, v101, v114, 7 bitop3:0x6c
	v_lshlrev_b32_e32 v217, 7, v101
	v_lshlrev_b32_e32 v100, 4, v100
	v_lshl_add_u32 v61, v61, 7, v121
	v_add3_u32 v86, 0, v100, v217
	v_bitop3_b32 v100, v101, v118, 7 bitop3:0x6c
	v_lshlrev_b32_e32 v100, 4, v100
	v_add3_u32 v87, 0, v100, v217
	v_add_u32_e32 v100, 0x3fc, v61
	v_add_u32_e32 v101, 0x43c, v61
	v_cndmask_b32_e64 v92, v100, v101, s[6:7]
	v_add_u32_e32 v100, 0x400, v61
	v_add_u32_e32 v101, 0x440, v61
	v_cndmask_b32_e64 v93, v100, v101, s[10:11]
	v_add_u32_e32 v100, 0x404, v61
	v_add_u32_e32 v101, 0x444, v61
	v_cndmask_b32_e64 v94, v100, v101, s[14:15]
	v_add_u32_e32 v100, 0x408, v61
	v_add_u32_e32 v101, 0x448, v61
	v_cndmask_b32_e64 v95, v100, v101, s[18:19]
	v_lshl_add_u32 v217, v216, 7, v120
	v_bitop3_b32 v100, v216, v134, 7 bitop3:0x6c
	v_lshl_add_u32 v88, v100, 4, v217
	v_bitop3_b32 v100, v216, v135, 7 bitop3:0x6c
	v_lshl_add_u32 v89, v100, 4, v217
	v_bitop3_b32 v100, v216, v136, 7 bitop3:0x6c
	v_lshl_add_u32 v90, v100, 4, v217
	v_bitop3_b32 v100, v216, v137, 7 bitop3:0x6c
	v_lshl_add_u32 v91, v100, 4, v217
	s_lshl_b32 s26, s50, 15
	v_ashrrev_i32_e32 v61, 31, v60
	v_lshlrev_b64 v[60:61], 19, v[60:61]
	v_lshl_add_u64 v[60:61], s[40:41], 0, v[60:61]
	v_lshl_add_u64 v[60:61], v[60:61], 0, s[26:27]
	v_lshl_add_u64 v[60:61], v[60:61], 0, v[58:59]
	v_lshlrev_b32_e32 v58, 1, v104
	v_lshl_add_u64 v[60:61], v[60:61], 0, v[58:59]
	v_lshl_add_u64 v[60:61], v[60:61], 0, s[28:29]
	s_mov_b32 s58, s57
	s_mov_b32 s59, s56
	s_mov_b32 s72, s55
	ds_read_b32 v156, v92 offset:0
	ds_read_b32 v157, v93 offset:0
	ds_read_b32 v158, v94 offset:0
	ds_read_b32 v159, v95 offset:0
	ds_read_b128 v[204:207], v86 offset:0
	ds_read_b128 v[208:211], v86 offset:2048
	ds_read_b128 v[212:215], v87 offset:0
	ds_read_b128 v[220:223], v87 offset:2048
	s_waitcnt lgkmcnt(7)
	ds_read_b32 v160, v92 offset:128
	ds_read_b32 v161, v93 offset:128
	ds_read_b32 v162, v94 offset:128
	ds_read_b32 v163, v95 offset:128
	ds_read_b128 v[224:227], v86 offset:8192
	ds_read_b128 v[228:231], v86 offset:10240
	ds_read_b128 v[232:235], v87 offset:8192
	ds_read_b128 v[236:239], v87 offset:10240
	s_waitcnt vmcnt(14)
	s_waitcnt lgkmcnt(11)
	v_mfma_f32_16x16x32_bf16 v[188:191], v[204:207], v[82:85], v[156:159]
	s_waitcnt lgkmcnt(10)
	v_mfma_f32_16x16x32_bf16 v[192:195], v[208:211], v[82:85], v[156:159]
	s_waitcnt lgkmcnt(9)
	v_mfma_f32_16x16x32_bf16 v[188:191], v[212:215], v[78:81], v[188:191]
	s_waitcnt lgkmcnt(8)
	v_mfma_f32_16x16x32_bf16 v[192:195], v[220:223], v[78:81], v[192:195]
	s_waitcnt lgkmcnt(7)
	ds_read_b32 v164, v92 offset:256
	ds_read_b32 v165, v93 offset:256
	ds_read_b32 v166, v94 offset:256
	ds_read_b32 v167, v95 offset:256
	ds_read_b128 v[240:243], v86 offset:16384
	ds_read_b128 v[144:147], v86 offset:18432
	ds_read_b128 v[148:151], v87 offset:16384
	ds_read_b128 v[152:155], v87 offset:18432
	s_waitcnt lgkmcnt(11)
	v_mfma_f32_16x16x32_bf16 v[196:199], v[224:227], v[82:85], v[160:163]
	s_waitcnt lgkmcnt(10)
	v_mfma_f32_16x16x32_bf16 v[200:203], v[228:231], v[82:85], v[160:163]
	s_waitcnt lgkmcnt(9)
	v_mfma_f32_16x16x32_bf16 v[196:199], v[232:235], v[78:81], v[196:199]
	s_waitcnt lgkmcnt(8)
	v_mfma_f32_16x16x32_bf16 v[200:203], v[236:239], v[78:81], v[200:203]
	s_waitcnt lgkmcnt(7)
	ds_read_b32 v168, v92 offset:384
	ds_read_b32 v169, v93 offset:384
	ds_read_b32 v170, v94 offset:384
	ds_read_b32 v171, v95 offset:384
	ds_read_b128 v[204:207], v86 offset:24576
	ds_read_b128 v[208:211], v86 offset:26624
	ds_read_b128 v[212:215], v87 offset:24576
	ds_read_b128 v[220:223], v87 offset:26624
	v_cndmask_b32_e64 v156, v188, v192, s[6:7]
	v_cndmask_b32_e64 v157, v189, v193, s[10:11]
	v_cndmask_b32_e64 v158, v190, v194, s[14:15]
	v_cndmask_b32_e64 v159, v191, v195, s[18:19]
	s_waitcnt lgkmcnt(11)
	v_mfma_f32_16x16x32_bf16 v[188:191], v[240:243], v[82:85], v[164:167]
	s_waitcnt lgkmcnt(10)
	v_mfma_f32_16x16x32_bf16 v[192:195], v[144:147], v[82:85], v[164:167]
	s_waitcnt lgkmcnt(9)
	v_mfma_f32_16x16x32_bf16 v[188:191], v[148:151], v[78:81], v[188:191]
	s_waitcnt lgkmcnt(8)
	v_mfma_f32_16x16x32_bf16 v[192:195], v[152:155], v[78:81], v[192:195]
	s_waitcnt lgkmcnt(7)
	ds_read_b32 v172, v92 offset:512
	ds_read_b32 v173, v93 offset:512
	ds_read_b32 v174, v94 offset:512
	ds_read_b32 v175, v95 offset:512
	ds_read_b128 v[224:227], v86 offset:32768
	ds_read_b128 v[228:231], v86 offset:34816
	ds_read_b128 v[232:235], v87 offset:32768
	ds_read_b128 v[236:239], v87 offset:34816
	v_cndmask_b32_e64 v160, v196, v200, s[6:7]
	v_cndmask_b32_e64 v161, v197, v201, s[10:11]
	v_cndmask_b32_e64 v162, v198, v202, s[14:15]
	v_cndmask_b32_e64 v163, v199, v203, s[18:19]
	s_waitcnt lgkmcnt(11)
	v_mfma_f32_16x16x32_bf16 v[196:199], v[204:207], v[82:85], v[168:171]
	s_waitcnt lgkmcnt(10)
	v_mfma_f32_16x16x32_bf16 v[200:203], v[208:211], v[82:85], v[168:171]
	s_waitcnt lgkmcnt(9)
	v_mfma_f32_16x16x32_bf16 v[196:199], v[212:215], v[78:81], v[196:199]
	s_waitcnt lgkmcnt(8)
; #define LAS __attribute__((address_space(3)))
; __device__ __forceinline__ void attn_b_unit(LAS unsigned char* lds, const bf16* Z, bf16* Y, int unit) {
;     ...
;     const LAS float* tpa[4]; const LAS float* tpb[4];
; #pragma unroll
;     for (int r = 0; r < 4; ++r) { const int kca = kcl + r, kcb = kca + 16;
;         tpa[r] = (kca >= cs && kca <= cs + 15) ? T0 + r : T + B_TREAL; tpb[r] = (kcb >= cs && kcb <= cs + 15) ? T0 + 16 + r : T + B_TREAL; }
; #pragma unroll
;     for (int st = 0; st < 4; ++st) {
;         const int offA = st * 8192, offB = offA + 4 * 8192;
;         f32x4 SA0, SA1, SB0, SB1;
;         qk_at(kp0, kp1, offA, qf0, qf1, SA0, SA1);
;         qk_at(kp0, kp1, offB, qf0, qf1, SB0, SB1);
; #pragma unroll
;         for (int r = 0; r < 4; ++r) {
;             SA0[r] += tpa[r][st * 32]; SA1[r] += tpb[r][st * 32]; SB0[r] += tpa[r][st * 32 + 128]; SB1[r] += tpb[r][st * 32 + 128];
;         }
;         softmax_step(SA0, SA1, m0, l0, O0);
;         softmax_step(SB0, SB1, m1, l1, O1);
;         pv_at(vp, offA, SA0, SA1, O0);
;         pv_at(vp, offB, SB0, SB1, O1);
;     }
	v_mfma_f32_16x16x32_bf16 v[200:203], v[220:223], v[78:81], v[200:203]
	s_waitcnt lgkmcnt(7)
	ds_read_b32 v176, v92 offset:640
	ds_read_b32 v177, v93 offset:640
	ds_read_b32 v178, v94 offset:640
	ds_read_b32 v179, v95 offset:640
	ds_read_b128 v[240:243], v86 offset:40960
	ds_read_b128 v[144:147], v86 offset:43008
	ds_read_b128 v[148:151], v87 offset:40960
	ds_read_b128 v[152:155], v87 offset:43008
	v_cndmask_b32_e64 v164, v188, v192, s[6:7]
	v_cndmask_b32_e64 v165, v189, v193, s[10:11]
	v_cndmask_b32_e64 v166, v190, v194, s[14:15]
	v_cndmask_b32_e64 v167, v191, v195, s[18:19]
	s_waitcnt lgkmcnt(11)
	v_mfma_f32_16x16x32_bf16 v[188:191], v[224:227], v[82:85], v[172:175]
	s_waitcnt lgkmcnt(10)
	v_mfma_f32_16x16x32_bf16 v[192:195], v[228:231], v[82:85], v[172:175]
	s_waitcnt lgkmcnt(9)
	v_mfma_f32_16x16x32_bf16 v[188:191], v[232:235], v[78:81], v[188:191]
	s_waitcnt lgkmcnt(8)
	v_mfma_f32_16x16x32_bf16 v[192:195], v[236:239], v[78:81], v[192:195]
	s_waitcnt lgkmcnt(7)
	ds_read_b32 v180, v92 offset:768
	ds_read_b32 v181, v93 offset:768
	ds_read_b32 v182, v94 offset:768
	ds_read_b32 v183, v95 offset:768
	ds_read_b128 v[204:207], v86 offset:49152
	ds_read_b128 v[208:211], v86 offset:51200
	ds_read_b128 v[212:215], v87 offset:49152
	ds_read_b128 v[220:223], v87 offset:51200
	v_cndmask_b32_e64 v168, v196, v200, s[6:7]
	v_cndmask_b32_e64 v169, v197, v201, s[10:11]
	v_cndmask_b32_e64 v170, v198, v202, s[14:15]
	v_cndmask_b32_e64 v171, v199, v203, s[18:19]
	s_waitcnt lgkmcnt(11)
	v_mfma_f32_16x16x32_bf16 v[196:199], v[240:243], v[82:85], v[176:179]
	s_waitcnt lgkmcnt(10)
	v_mfma_f32_16x16x32_bf16 v[200:203], v[144:147], v[82:85], v[176:179]
	s_waitcnt lgkmcnt(9)
	v_mfma_f32_16x16x32_bf16 v[196:199], v[148:151], v[78:81], v[196:199]
	s_waitcnt lgkmcnt(8)
	v_mfma_f32_16x16x32_bf16 v[200:203], v[152:155], v[78:81], v[200:203]
	s_waitcnt lgkmcnt(7)
	ds_read_b32 v184, v92 offset:896
	ds_read_b32 v185, v93 offset:896
	ds_read_b32 v186, v94 offset:896
	ds_read_b32 v187, v95 offset:896
	ds_read_b128 v[224:227], v86 offset:57344
	ds_read_b128 v[228:231], v86 offset:59392
	ds_read_b128 v[232:235], v87 offset:57344
	ds_read_b128 v[236:239], v87 offset:59392
	v_cndmask_b32_e64 v172, v188, v192, s[6:7]
	v_cndmask_b32_e64 v173, v189, v193, s[10:11]
	v_cndmask_b32_e64 v174, v190, v194, s[14:15]
	v_cndmask_b32_e64 v175, v191, v195, s[18:19]
	s_waitcnt lgkmcnt(11)
	v_mfma_f32_16x16x32_bf16 v[188:191], v[204:207], v[82:85], v[180:183]
	s_waitcnt lgkmcnt(10)
	v_mfma_f32_16x16x32_bf16 v[192:195], v[208:211], v[82:85], v[180:183]
	s_waitcnt lgkmcnt(9)
	v_mfma_f32_16x16x32_bf16 v[188:191], v[212:215], v[78:81], v[188:191]
	s_waitcnt lgkmcnt(8)
	v_mfma_f32_16x16x32_bf16 v[192:195], v[220:223], v[78:81], v[192:195]
	v_cndmask_b32_e64 v176, v196, v200, s[6:7]
	v_cndmask_b32_e64 v177, v197, v201, s[10:11]
	v_cndmask_b32_e64 v178, v198, v202, s[14:15]
	v_cndmask_b32_e64 v179, v199, v203, s[18:19]
	s_waitcnt lgkmcnt(3)
	v_mfma_f32_16x16x32_bf16 v[196:199], v[224:227], v[82:85], v[184:187]
	s_waitcnt lgkmcnt(2)
	v_mfma_f32_16x16x32_bf16 v[200:203], v[228:231], v[82:85], v[184:187]
	s_waitcnt lgkmcnt(1)
	v_mfma_f32_16x16x32_bf16 v[196:199], v[232:235], v[78:81], v[196:199]
	s_waitcnt lgkmcnt(0)
	v_mfma_f32_16x16x32_bf16 v[200:203], v[236:239], v[78:81], v[200:203]
	v_cndmask_b32_e64 v180, v188, v192, s[6:7]
	v_cndmask_b32_e64 v181, v189, v193, s[10:11]
	v_cndmask_b32_e64 v182, v190, v194, s[14:15]
	v_cndmask_b32_e64 v183, v191, v195, s[18:19]
	ds_read_b64_tr_b16 v[212:213], v88 offset:0
	ds_read_b64_tr_b16 v[214:215], v88 offset:2048
	ds_read_b64_tr_b16 v[220:221], v89 offset:0
	ds_read_b64_tr_b16 v[222:223], v89 offset:2048
	ds_read_b64_tr_b16 v[224:225], v90 offset:0
	ds_read_b64_tr_b16 v[226:227], v90 offset:2048
	ds_read_b64_tr_b16 v[228:229], v91 offset:0
	ds_read_b64_tr_b16 v[230:231], v91 offset:2048
	v_mov_b32_e32 v100, 0xffff
	v_mov_b32_e32 v101, 0xffff0000
	v_cndmask_b32_e64 v96, v100, 0, s[6:7]
	v_cndmask_b32_e64 v216, v101, 0, s[10:11]
	v_cndmask_b32_e64 v97, v100, 0, s[14:15]
	v_cndmask_b32_e64 v217, v101, 0, s[18:19]
	v_cndmask_b32_e64 v184, v196, v200, s[6:7]
	v_cndmask_b32_e64 v185, v197, v201, s[10:11]
	v_cndmask_b32_e64 v186, v198, v202, s[14:15]
	v_cndmask_b32_e64 v187, v199, v203, s[18:19]
	v_or_b32_e32 v96, v96, v216
	v_or_b32_e32 v97, v97, v217
	v_not_b32_e32 v98, v96
	v_not_b32_e32 v99, v97
	s_waitcnt lgkmcnt(7)
; #define LAS __attribute__((address_space(3)))
; __device__ __forceinline__ unsigned pk2(float lo, float hi) { return pg8::cvt_pk_bf16(lo, hi); }
; __device__ __forceinline__ s16x4 vtr(const LAS unsigned char* p) { return __builtin_bit_cast(s16x4, __builtin_amdgcn_ds_read_tr16_b64_v4i16((LAS s16x4*)p)); }
; #define MFMA16(a, b, c) __builtin_amdgcn_mfma_f32_16x16x32_bf16((a), (b), (c), 0, 0, 0)
; __device__ __forceinline__ void pv_at(const LAS unsigned char* const (&vp)[4], int off, const f32x4& P0, const f32x4& P1, f32x4 (&O)[4]) {
;     v4u pw; pw.x = pk2(P0[0], P0[1]); pw.y = pk2(P0[2], P0[3]); pw.z = pk2(P1[0], P1[1]); pw.w = pk2(P1[2], P1[3]);
;     const bf16x8 pb = __builtin_bit_cast(bf16x8, pw);
; #pragma unroll
;     for (int db = 0; db < 4; ++db) {
;         const s16x4 lo = vtr(vp[db] + off), hi = vtr(vp[db] + off + 2048);
;         const bf16x8 vt = (bf16x8){lo[0], lo[1], lo[2], lo[3], hi[0], hi[1], hi[2], hi[3]};
;         O[db] = MFMA16(vt, pb, O[db]);
;     }
; }
; __device__ __forceinline__ void softmax_step(f32x4& s0, f32x4& s1, float& m, float& l, f32x4 (&O)[4]) {
;     float t = fmaxf(fmaxf(fmaxf(s0[0], s0[1]), fmaxf(s0[2], s0[3])), fmaxf(fmaxf(s1[0], s1[1]), fmaxf(s1[2], s1[3])));
;     t = xrow16_max(t);
;     const float mn = fmaxf(m, t), alpha = __builtin_amdgcn_exp2f(m - mn);
;     m = mn;
; #pragma unroll
;     for (int k = 0; k < 4; ++k) { s0[k] = __builtin_amdgcn_exp2f(s0[k] - mn); s1[k] = __builtin_amdgcn_exp2f(s1[k] - mn); }
;     l = l * alpha + ((s0[0] + s0[1]) + (s0[2] + s0[3])) + ((s1[0] + s1[1]) + (s1[2] + s1[3]));
; #pragma unroll
;     for (int db = 0; db < 4; ++db) O[db] *= alpha;
; }
	ds_read_b64_tr_b16 v[232:233], v88 offset:8192
	ds_read_b64_tr_b16 v[234:235], v88 offset:10240
	ds_read_b64_tr_b16 v[236:237], v89 offset:8192
	ds_read_b64_tr_b16 v[238:239], v89 offset:10240
	ds_read_b64_tr_b16 v[240:241], v90 offset:8192
	ds_read_b64_tr_b16 v[242:243], v90 offset:10240
	ds_read_b64_tr_b16 v[144:145], v91 offset:8192
	ds_read_b64_tr_b16 v[146:147], v91 offset:10240
	v_max3_f32 v142, v156, v157, v158
	v_max3_f32 v143, v164, v165, v166
	v_max3_f32 v216, v172, v173, v174
	v_max3_f32 v217, v180, v181, v182
	v_max3_f32 v142, v142, v159, v160
	v_max3_f32 v143, v143, v167, v168
	v_max3_f32 v216, v216, v175, v176
	v_max3_f32 v217, v217, v183, v184
	v_max3_f32 v142, v142, v161, v162
	v_max3_f32 v143, v143, v169, v170
	v_max3_f32 v216, v216, v177, v178
	v_max3_f32 v217, v217, v185, v186
	v_max_f32_e32 v142, v142, v163
	v_max_f32_e32 v143, v143, v171
	v_max_f32_e32 v216, v216, v179
	v_max_f32_e32 v217, v217, v187
	v_max3_f32 v244, v142, v143, v216
	v_max_f32_e32 v244, v244, v217
	v_mov_b32_e32 v100, v244
	s_nop 1
	v_permlane16_swap_b32_e32 v244, v100
	v_max_f32_e32 v244, v244, v100
	v_mov_b32_e32 v100, v244
	s_nop 1
	v_permlane32_swap_b32_e32 v244, v100
	v_max3_f32 v244, v244, v100, s54
	v_pk_add_f32 v[156:157], v[156:157], v[244:245] op_sel_hi:[1,0] neg_lo:[0,1] neg_hi:[0,1]
	v_pk_add_f32 v[158:159], v[158:159], v[244:245] op_sel_hi:[1,0] neg_lo:[0,1] neg_hi:[0,1]
	v_pk_add_f32 v[160:161], v[160:161], v[244:245] op_sel_hi:[1,0] neg_lo:[0,1] neg_hi:[0,1]
	v_pk_add_f32 v[162:163], v[162:163], v[244:245] op_sel_hi:[1,0] neg_lo:[0,1] neg_hi:[0,1]
	v_pk_add_f32 v[164:165], v[164:165], v[244:245] op_sel_hi:[1,0] neg_lo:[0,1] neg_hi:[0,1]
	v_pk_add_f32 v[166:167], v[166:167], v[244:245] op_sel_hi:[1,0] neg_lo:[0,1] neg_hi:[0,1]
	v_pk_add_f32 v[168:169], v[168:169], v[244:245] op_sel_hi:[1,0] neg_lo:[0,1] neg_hi:[0,1]
	v_pk_add_f32 v[170:171], v[170:171], v[244:245] op_sel_hi:[1,0] neg_lo:[0,1] neg_hi:[0,1]
	v_pk_add_f32 v[172:173], v[172:173], v[244:245] op_sel_hi:[1,0] neg_lo:[0,1] neg_hi:[0,1]
	v_pk_add_f32 v[174:175], v[174:175], v[244:245] op_sel_hi:[1,0] neg_lo:[0,1] neg_hi:[0,1]
	v_pk_add_f32 v[176:177], v[176:177], v[244:245] op_sel_hi:[1,0] neg_lo:[0,1] neg_hi:[0,1]
	v_pk_add_f32 v[178:179], v[178:179], v[244:245] op_sel_hi:[1,0] neg_lo:[0,1] neg_hi:[0,1]
	v_pk_add_f32 v[180:181], v[180:181], v[244:245] op_sel_hi:[1,0] neg_lo:[0,1] neg_hi:[0,1]
	v_pk_add_f32 v[182:183], v[182:183], v[244:245] op_sel_hi:[1,0] neg_lo:[0,1] neg_hi:[0,1]
	v_pk_add_f32 v[184:185], v[184:185], v[244:245] op_sel_hi:[1,0] neg_lo:[0,1] neg_hi:[0,1]
	v_pk_add_f32 v[186:187], v[186:187], v[244:245] op_sel_hi:[1,0] neg_lo:[0,1] neg_hi:[0,1]
	v_exp_f32_e32 v156, v156
	v_exp_f32_e32 v157, v157
	v_exp_f32_e32 v158, v158
	v_exp_f32_e32 v159, v159
	v_exp_f32_e32 v160, v160
	v_exp_f32_e32 v161, v161
	v_exp_f32_e32 v162, v162
	v_exp_f32_e32 v163, v163
	v_exp_f32_e32 v164, v164
	v_exp_f32_e32 v165, v165
	v_exp_f32_e32 v166, v166
	v_exp_f32_e32 v167, v167
	v_exp_f32_e32 v168, v168
	v_exp_f32_e32 v169, v169
	v_exp_f32_e32 v170, v170
	v_exp_f32_e32 v171, v171
	v_exp_f32_e32 v172, v172
	v_exp_f32_e32 v173, v173
	v_exp_f32_e32 v174, v174
	v_exp_f32_e32 v175, v175
	v_exp_f32_e32 v176, v176
	v_exp_f32_e32 v177, v177
	v_exp_f32_e32 v178, v178
	v_exp_f32_e32 v179, v179
	v_exp_f32_e32 v180, v180
	v_exp_f32_e32 v181, v181
	v_exp_f32_e32 v182, v182
	v_exp_f32_e32 v183, v183
	v_exp_f32_e32 v184, v184
	v_exp_f32_e32 v185, v185
	v_exp_f32_e32 v186, v186
	v_exp_f32_e32 v187, v187
	v_pk_add_f32 v[148:149], v[156:157], v[158:159]
	v_pk_add_f32 v[150:151], v[164:165], v[166:167]
	v_pk_add_f32 v[152:153], v[172:173], v[174:175]
	v_pk_add_f32 v[154:155], v[180:181], v[182:183]
	v_pk_add_f32 v[148:149], v[148:149], v[160:161]
	v_pk_add_f32 v[150:151], v[150:151], v[168:169]
	v_pk_add_f32 v[152:153], v[152:153], v[176:177]
	v_pk_add_f32 v[154:155], v[154:155], v[184:185]
	v_pk_add_f32 v[148:149], v[148:149], v[162:163]
	v_pk_add_f32 v[150:151], v[150:151], v[170:171]
	v_pk_add_f32 v[152:153], v[152:153], v[178:179]
	v_pk_add_f32 v[154:155], v[154:155], v[186:187]
	v_pk_add_f32 v[148:149], v[148:149], v[150:151]
	v_pk_add_f32 v[152:153], v[152:153], v[154:155]
	v_pk_add_f32 v[148:149], v[148:149], v[152:153]
	v_add_f32_e32 v245, v148, v149
	v_cvt_pk_bf16_f32 v100, v156, v157
	v_cvt_pk_bf16_f32 v101, v158, v159
	v_and_b32_e32 v188, v100, v96
	v_and_b32_e32 v189, v101, v97
	v_and_b32_e32 v190, v100, v98
	v_and_b32_e32 v191, v101, v99
	s_nop 1
	s_waitcnt lgkmcnt(14)
	v_mfma_f32_16x16x32_bf16 v[196:199], v[212:215], v[188:191], 0
	s_waitcnt lgkmcnt(12)
	v_mfma_f32_16x16x32_bf16 v[200:203], v[220:223], v[188:191], 0
	s_waitcnt lgkmcnt(10)
	v_mfma_f32_16x16x32_bf16 v[204:207], v[224:227], v[188:191], 0
	s_waitcnt lgkmcnt(8)
	v_mfma_f32_16x16x32_bf16 v[208:211], v[228:231], v[188:191], 0
	v_cvt_pk_bf16_f32 v100, v160, v161
	v_cvt_pk_bf16_f32 v101, v162, v163
	v_and_b32_e32 v192, v100, v96
	v_and_b32_e32 v193, v101, v97
	v_and_b32_e32 v194, v100, v98
	v_and_b32_e32 v195, v101, v99
	s_waitcnt lgkmcnt(7)
	ds_read_b64_tr_b16 v[212:213], v88 offset:16384
	ds_read_b64_tr_b16 v[214:215], v88 offset:18432
	ds_read_b64_tr_b16 v[220:221], v89 offset:16384
	ds_read_b64_tr_b16 v[222:223], v89 offset:18432
	ds_read_b64_tr_b16 v[224:225], v90 offset:16384
	ds_read_b64_tr_b16 v[226:227], v90 offset:18432
	ds_read_b64_tr_b16 v[228:229], v91 offset:16384
	ds_read_b64_tr_b16 v[230:231], v91 offset:18432
	s_waitcnt lgkmcnt(14)
	v_mfma_f32_16x16x32_bf16 v[196:199], v[232:235], v[192:195], v[196:199]
	s_waitcnt lgkmcnt(12)
	v_mfma_f32_16x16x32_bf16 v[200:203], v[236:239], v[192:195], v[200:203]
	s_waitcnt lgkmcnt(10)
; #define LAS __attribute__((address_space(3)))
; __device__ __forceinline__ unsigned pk2(float lo, float hi) { return pg8::cvt_pk_bf16(lo, hi); }
; __device__ __forceinline__ s16x4 vtr(const LAS unsigned char* p) { return __builtin_bit_cast(s16x4, __builtin_amdgcn_ds_read_tr16_b64_v4i16((LAS s16x4*)p)); }
; #define MFMA16(a, b, c) __builtin_amdgcn_mfma_f32_16x16x32_bf16((a), (b), (c), 0, 0, 0)
; __device__ __forceinline__ void pv_at(const LAS unsigned char* const (&vp)[4], int off, const f32x4& P0, const f32x4& P1, f32x4 (&O)[4]) {
;     v4u pw; pw.x = pk2(P0[0], P0[1]); pw.y = pk2(P0[2], P0[3]); pw.z = pk2(P1[0], P1[1]); pw.w = pk2(P1[2], P1[3]);
;     const bf16x8 pb = __builtin_bit_cast(bf16x8, pw);
; #pragma unroll
;     for (int db = 0; db < 4; ++db) {
;         const s16x4 lo = vtr(vp[db] + off), hi = vtr(vp[db] + off + 2048);
;         const bf16x8 vt = (bf16x8){lo[0], lo[1], lo[2], lo[3], hi[0], hi[1], hi[2], hi[3]};
;         O[db] = MFMA16(vt, pb, O[db]);
;     }
; }
	v_mfma_f32_16x16x32_bf16 v[204:207], v[240:243], v[192:195], v[204:207]
	s_waitcnt lgkmcnt(8)
	v_mfma_f32_16x16x32_bf16 v[208:211], v[144:147], v[192:195], v[208:211]
	v_cvt_pk_bf16_f32 v100, v164, v165
	v_cvt_pk_bf16_f32 v101, v166, v167
	v_and_b32_e32 v188, v100, v96
	v_and_b32_e32 v189, v101, v97
	v_and_b32_e32 v190, v100, v98
	v_and_b32_e32 v191, v101, v99
	s_waitcnt lgkmcnt(7)
	ds_read_b64_tr_b16 v[232:233], v88 offset:24576
	ds_read_b64_tr_b16 v[234:235], v88 offset:26624
	ds_read_b64_tr_b16 v[236:237], v89 offset:24576
	ds_read_b64_tr_b16 v[238:239], v89 offset:26624
	ds_read_b64_tr_b16 v[240:241], v90 offset:24576
	ds_read_b64_tr_b16 v[242:243], v90 offset:26624
	ds_read_b64_tr_b16 v[144:145], v91 offset:24576
	ds_read_b64_tr_b16 v[146:147], v91 offset:26624
	s_waitcnt lgkmcnt(14)
	v_mfma_f32_16x16x32_bf16 v[196:199], v[212:215], v[188:191], v[196:199]
	s_waitcnt lgkmcnt(12)
	v_mfma_f32_16x16x32_bf16 v[200:203], v[220:223], v[188:191], v[200:203]
	s_waitcnt lgkmcnt(10)
	v_mfma_f32_16x16x32_bf16 v[204:207], v[224:227], v[188:191], v[204:207]
	s_waitcnt lgkmcnt(8)
	v_mfma_f32_16x16x32_bf16 v[208:211], v[228:231], v[188:191], v[208:211]
	v_cvt_pk_bf16_f32 v100, v168, v169
	v_cvt_pk_bf16_f32 v101, v170, v171
	v_and_b32_e32 v192, v100, v96
	v_and_b32_e32 v193, v101, v97
	v_and_b32_e32 v194, v100, v98
	v_and_b32_e32 v195, v101, v99
	s_waitcnt lgkmcnt(7)
	ds_read_b64_tr_b16 v[212:213], v88 offset:32768
	ds_read_b64_tr_b16 v[214:215], v88 offset:34816
	ds_read_b64_tr_b16 v[220:221], v89 offset:32768
	ds_read_b64_tr_b16 v[222:223], v89 offset:34816
	ds_read_b64_tr_b16 v[224:225], v90 offset:32768
	ds_read_b64_tr_b16 v[226:227], v90 offset:34816
	ds_read_b64_tr_b16 v[228:229], v91 offset:32768
	ds_read_b64_tr_b16 v[230:231], v91 offset:34816
	s_waitcnt lgkmcnt(14)
	v_mfma_f32_16x16x32_bf16 v[196:199], v[232:235], v[192:195], v[196:199]
	s_waitcnt lgkmcnt(12)
	v_mfma_f32_16x16x32_bf16 v[200:203], v[236:239], v[192:195], v[200:203]
	s_waitcnt lgkmcnt(10)
	v_mfma_f32_16x16x32_bf16 v[204:207], v[240:243], v[192:195], v[204:207]
	s_waitcnt lgkmcnt(8)
	v_mfma_f32_16x16x32_bf16 v[208:211], v[144:147], v[192:195], v[208:211]
	v_cvt_pk_bf16_f32 v100, v172, v173
	v_cvt_pk_bf16_f32 v101, v174, v175
	v_and_b32_e32 v188, v100, v96
	v_and_b32_e32 v189, v101, v97
	v_and_b32_e32 v190, v100, v98
	v_and_b32_e32 v191, v101, v99
	s_waitcnt lgkmcnt(7)
	ds_read_b64_tr_b16 v[232:233], v88 offset:40960
	ds_read_b64_tr_b16 v[234:235], v88 offset:43008
	ds_read_b64_tr_b16 v[236:237], v89 offset:40960
	ds_read_b64_tr_b16 v[238:239], v89 offset:43008
	ds_read_b64_tr_b16 v[240:241], v90 offset:40960
	ds_read_b64_tr_b16 v[242:243], v90 offset:43008
	ds_read_b64_tr_b16 v[144:145], v91 offset:40960
	ds_read_b64_tr_b16 v[146:147], v91 offset:43008
	s_waitcnt lgkmcnt(14)
	v_mfma_f32_16x16x32_bf16 v[196:199], v[212:215], v[188:191], v[196:199]
	s_waitcnt lgkmcnt(12)
	v_mfma_f32_16x16x32_bf16 v[200:203], v[220:223], v[188:191], v[200:203]
	s_waitcnt lgkmcnt(10)
	v_mfma_f32_16x16x32_bf16 v[204:207], v[224:227], v[188:191], v[204:207]
	s_waitcnt lgkmcnt(8)
	v_mfma_f32_16x16x32_bf16 v[208:211], v[228:231], v[188:191], v[208:211]
	v_cvt_pk_bf16_f32 v100, v176, v177
	v_cvt_pk_bf16_f32 v101, v178, v179
	v_and_b32_e32 v192, v100, v96
	v_and_b32_e32 v193, v101, v97
	v_and_b32_e32 v194, v100, v98
	v_and_b32_e32 v195, v101, v99
	s_waitcnt lgkmcnt(7)
	ds_read_b64_tr_b16 v[212:213], v88 offset:49152
	ds_read_b64_tr_b16 v[214:215], v88 offset:51200
	ds_read_b64_tr_b16 v[220:221], v89 offset:49152
	ds_read_b64_tr_b16 v[222:223], v89 offset:51200
	ds_read_b64_tr_b16 v[224:225], v90 offset:49152
	ds_read_b64_tr_b16 v[226:227], v90 offset:51200
	ds_read_b64_tr_b16 v[228:229], v91 offset:49152
	ds_read_b64_tr_b16 v[230:231], v91 offset:51200
	s_waitcnt lgkmcnt(14)
; #define LAS __attribute__((address_space(3)))
; __device__ __forceinline__ unsigned pk2(float lo, float hi) { return pg8::cvt_pk_bf16(lo, hi); }
; __device__ __forceinline__ s16x4 vtr(const LAS unsigned char* p) { return __builtin_bit_cast(s16x4, __builtin_amdgcn_ds_read_tr16_b64_v4i16((LAS s16x4*)p)); }
; #define MFMA16(a, b, c) __builtin_amdgcn_mfma_f32_16x16x32_bf16((a), (b), (c), 0, 0, 0)
; __device__ __forceinline__ void pv_at(const LAS unsigned char* const (&vp)[4], int off, const f32x4& P0, const f32x4& P1, f32x4 (&O)[4]) {
;     v4u pw; pw.x = pk2(P0[0], P0[1]); pw.y = pk2(P0[2], P0[3]); pw.z = pk2(P1[0], P1[1]); pw.w = pk2(P1[2], P1[3]);
;     const bf16x8 pb = __builtin_bit_cast(bf16x8, pw);
; #pragma unroll
;     for (int db = 0; db < 4; ++db) {
;         const s16x4 lo = vtr(vp[db] + off), hi = vtr(vp[db] + off + 2048);
;         const bf16x8 vt = (bf16x8){lo[0], lo[1], lo[2], lo[3], hi[0], hi[1], hi[2], hi[3]};
;         O[db] = MFMA16(vt, pb, O[db]);
;     }
; }
; __device__ __forceinline__ void store_o(bf16* yrow, int g, float l, const f32x4 (&O)[4]) {
;     const float inv = 1.0f / xrow16_sum(l);
;     unsigned wx[4], wy[4];
; #pragma unroll
;     for (int db = 0; db < 4; ++db) { wx[db] = pk2(O[db][0] * inv, O[db][1] * inv); wy[db] = pk2(O[db][2] * inv, O[db][3] * inv); }
; #pragma unroll
;     for (int p = 0; p < 2; ++p) {
;         auto rx = __builtin_amdgcn_permlane16_swap(wx[2 * p], wx[2 * p + 1], false, false); wx[2 * p] = rx[0]; wx[2 * p + 1] = rx[1];
;         auto ry = __builtin_amdgcn_permlane16_swap(wy[2 * p], wy[2 * p + 1], false, false); wy[2 * p] = ry[0]; wy[2 * p + 1] = ry[1]; }
; #pragma unroll
;     for (int p = 0; p < 2; ++p) {
;         auto rx = __builtin_amdgcn_permlane32_swap(wx[p], wx[p + 2], false, false); wx[p] = rx[0]; wx[p + 2] = rx[1];
;         auto ry = __builtin_amdgcn_permlane32_swap(wy[p], wy[p + 2], false, false); wy[p] = ry[0]; wy[p + 2] = ry[1]; }
;     v4u lo = {wx[0], wy[0], wx[1], wy[1]}, hi = {wx[2], wy[2], wx[3], wy[3]};
;     *(v4u*)(yrow + 16 * g) = lo; *(v4u*)(yrow + 16 * g + 8) = hi;
; }
	v_mfma_f32_16x16x32_bf16 v[196:199], v[232:235], v[192:195], v[196:199]
	s_waitcnt lgkmcnt(12)
	v_mfma_f32_16x16x32_bf16 v[200:203], v[236:239], v[192:195], v[200:203]
	s_waitcnt lgkmcnt(10)
	v_mfma_f32_16x16x32_bf16 v[204:207], v[240:243], v[192:195], v[204:207]
	s_waitcnt lgkmcnt(8)
	v_mfma_f32_16x16x32_bf16 v[208:211], v[144:147], v[192:195], v[208:211]
	v_cvt_pk_bf16_f32 v100, v180, v181
	v_cvt_pk_bf16_f32 v101, v182, v183
	v_and_b32_e32 v188, v100, v96
	v_and_b32_e32 v189, v101, v97
	v_and_b32_e32 v190, v100, v98
	v_and_b32_e32 v191, v101, v99
	s_waitcnt lgkmcnt(7)
	ds_read_b64_tr_b16 v[232:233], v88 offset:57344
	ds_read_b64_tr_b16 v[234:235], v88 offset:59392
	ds_read_b64_tr_b16 v[236:237], v89 offset:57344
	ds_read_b64_tr_b16 v[238:239], v89 offset:59392
	ds_read_b64_tr_b16 v[240:241], v90 offset:57344
	ds_read_b64_tr_b16 v[242:243], v90 offset:59392
	ds_read_b64_tr_b16 v[144:145], v91 offset:57344
	ds_read_b64_tr_b16 v[146:147], v91 offset:59392
	s_waitcnt lgkmcnt(14)
	v_mfma_f32_16x16x32_bf16 v[196:199], v[212:215], v[188:191], v[196:199]
	s_waitcnt lgkmcnt(12)
	v_mfma_f32_16x16x32_bf16 v[200:203], v[220:223], v[188:191], v[200:203]
	s_waitcnt lgkmcnt(10)
	v_mfma_f32_16x16x32_bf16 v[204:207], v[224:227], v[188:191], v[204:207]
	s_waitcnt lgkmcnt(8)
	v_mfma_f32_16x16x32_bf16 v[208:211], v[228:231], v[188:191], v[208:211]
	v_cvt_pk_bf16_f32 v100, v184, v185
	v_cvt_pk_bf16_f32 v101, v186, v187
	v_and_b32_e32 v192, v100, v96
	v_and_b32_e32 v193, v101, v97
	v_and_b32_e32 v194, v100, v98
	v_and_b32_e32 v195, v101, v99
	s_nop 1
	s_waitcnt lgkmcnt(6)
	v_mfma_f32_16x16x32_bf16 v[196:199], v[232:235], v[192:195], v[196:199]
	s_waitcnt lgkmcnt(4)
	v_mfma_f32_16x16x32_bf16 v[200:203], v[236:239], v[192:195], v[200:203]
	s_waitcnt lgkmcnt(2)
	v_mfma_f32_16x16x32_bf16 v[204:207], v[240:243], v[192:195], v[204:207]
	s_waitcnt lgkmcnt(0)
	v_mfma_f32_16x16x32_bf16 v[208:211], v[144:147], v[192:195], v[208:211]
	v_mov_b32_e32 v100, v245
	s_nop 1
	v_permlane16_swap_b32_e32 v245, v100
	v_add_f32_e32 v245, v245, v100
	v_mov_b32_e32 v100, v245
	s_nop 1
	v_permlane32_swap_b32_e32 v245, v100
	v_add_f32_e32 v245, v245, v100
	v_div_scale_f32 v142, s[50:51], v245, v245, 1.0
	v_div_scale_f32 v216, vcc, 1.0, v245, 1.0
	v_rcp_f32_e32 v143, v142
	s_nop 0
	v_fma_f32 v217, -v142, v143, 1.0
	v_fmac_f32_e32 v143, v217, v143
	v_mul_f32_e32 v148, v216, v143
	v_fma_f32 v149, -v142, v148, v216
	v_fmac_f32_e32 v148, v149, v143
	v_fma_f32 v216, -v142, v148, v216
	v_div_fmas_f32 v216, v216, v143, v148
	v_div_fixup_f32 v216, v216, v245, 1.0
	v_mul_f32_e32 v100, v196, v216
	v_mul_f32_e32 v101, v197, v216
	v_mul_f32_e32 v142, v198, v216
	v_mul_f32_e32 v143, v199, v216
	v_cvt_pk_bf16_f32 v78, v100, v101
	v_cvt_pk_bf16_f32 v79, v142, v143
	v_mul_f32_e32 v100, v200, v216
	v_mul_f32_e32 v101, v201, v216
	v_mul_f32_e32 v142, v202, v216
	v_mul_f32_e32 v143, v203, v216
	v_cvt_pk_bf16_f32 v80, v100, v101
	v_cvt_pk_bf16_f32 v81, v142, v143
	v_mul_f32_e32 v100, v204, v216
	v_mul_f32_e32 v101, v205, v216
	v_mul_f32_e32 v142, v206, v216
	v_mul_f32_e32 v143, v207, v216
	v_cvt_pk_bf16_f32 v82, v100, v101
	v_cvt_pk_bf16_f32 v83, v142, v143
	v_mul_f32_e32 v100, v208, v216
	v_mul_f32_e32 v101, v209, v216
	v_mul_f32_e32 v142, v210, v216
	v_mul_f32_e32 v143, v211, v216
	v_cvt_pk_bf16_f32 v84, v100, v101
	v_cvt_pk_bf16_f32 v85, v142, v143
	s_nop 1
	v_permlane16_swap_b32_e32 v78, v80
	v_permlane16_swap_b32_e32 v79, v81
	v_permlane16_swap_b32_e32 v82, v84
	v_permlane16_swap_b32_e32 v83, v85
	s_nop 0
	v_permlane32_swap_b32_e32 v78, v82
	v_permlane32_swap_b32_e32 v79, v83
	v_permlane32_swap_b32_e32 v80, v84
	v_permlane32_swap_b32_e32 v81, v85
	s_andn2_b64 vcc, exec, s[44:45]
	global_store_dwordx4 v[60:61], v[78:81], off
	global_store_dwordx4 v[60:61], v[82:85], off offset:16
	s_barrier
	s_cbranch_vccz .LBB0_294
